# v83 + non-blocking entry arrival: arrival atomic returns into spare VGPRs, last-arriver release done mid-P0, poll before B1
# baseline (speedup 1.0000x reference)
; #define LAS __attribute__((address_space(3)))
; __global__ void __launch_bounds__(NTHR, 2) fwd_kernel(Args a) {
;     ...
;     if (threadIdx.x < 64) ((LAS unsigned*)(lds + 131072))[threadIdx.x] = 0u;
;     if (bx == 0) for (int i = threadIdx.x; i < XCD_BAR_WORDS; i += NTHR) __hip_atomic_store((unsigned*)(a.ws + 16384) + i, 0u, __ATOMIC_RELAXED, __HIP_MEMORY_SCOPE_AGENT);
;     __syncthreads();
;     grid.sync();
;     const XcdBarrier xbar = xcd_barrier_post((unsigned*)(a.ws + 16384), (volatile LAS unsigned*)(lds + 131072 + 32));
.LBB0_6:
	v_lshrrev_b32_e32 v1, 20, v0
	v_lshrrev_b32_e32 v0, 10, v0
	v_or_b32_e32 v0, v0, v1
	s_movk_i32 s2, 0x3ff
	v_and_or_b32 v0, v0, s2, v189
	v_cmp_eq_u32_e32 vcc, 0, v0
	s_waitcnt vmcnt(0)
	s_barrier
	s_barrier
	s_and_saveexec_b64 s[2:3], vcc
	s_cbranch_execz .LBB0_16
	s_waitcnt vmcnt(0)
	s_load_dwordx2 s[4:5], s[4:5], 0x58
	v_mov_b32_e32 v2, 0
	s_mov_b64 s[6:7], exec
	v_mbcnt_lo_u32_b32 v1, s6, 0
	v_mbcnt_hi_u32_b32 v1, s7, v1
	s_waitcnt lgkmcnt(0)
	global_load_dword v100, v2, s[4:5] offset:40
	v_mov_b32_e32 v3, 1
	global_atomic_add v101, v2, v3, s[4:5] offset:32 sc0
	v_writelane_b32 v255, s4, 41
	v_writelane_b32 v255, s5, 42

; __device__ __forceinline__ float sigmoidf_(float x) { return __builtin_amdgcn_rcpf(1.f + __expf(-x)); }
; __global__ void __launch_bounds__(NTHR, 2) fwd_kernel(Args a) {
;     ...
;     grid.sync();
;     ...
;         __syncthreads();
;         for (int i = tid; i < 5 * DM; i += NTHR) { const float c = i < 4 * DM ? a.in[I_C][i] : a.in[I_CCTX][i - 4 * DM]; sl[i] = c * sigmoidf_(c); }
;         __syncthreads();
;         for (int cb = bx; cb < 256; cb += G) {
;             const int col = cb * 48 + (lane < 48 ? lane : 47);
;             float acc[5] = {0.f, 0.f, 0.f, 0.f, 0.f};
;             const float* wp = a.in[I_WADA] + (size_t)(wave * 256) * MODW + col;
; #pragma unroll 16
;             for (int kk = 0; kk < 256; ++kk) {
.LBB0_100:
	s_or_b64 exec, exec, s[0:1]
	v_cmp_eq_u32_e32 vcc, 0, v189
	s_and_saveexec_b64 s[100:101], vcc
	s_cbranch_execz .Lcga_skip
	s_waitcnt vmcnt(0)
	v_add_u32_e32 v102, -1, v100
	v_and_b32_e32 v103, 0xffff, v101
	v_cmp_eq_u32_e32 vcc, v103, v102
	s_cbranch_vccz .Lcga_nolast
	v_sub_u32_e32 v102, 0x10000, v100
	v_mov_b32_e32 v103, 0
	v_readlane_b32 s98, v255, 41
	v_readlane_b32 s99, v255, 42
	s_nop 4
	global_atomic_add v103, v102, s[98:99] offset:32
.Lcga_nolast:
	v_and_b32_e32 v101, 0xffff0000, v101
	s_nop 1
	v_readfirstlane_b32 s98, v101
	s_nop 3
	v_writelane_b32 v255, s98, 40
.Lcga_skip:
	s_or_b64 exec, exec, s[100:101]
	s_add_u32 s68, s66, 0x10000
	s_addc_u32 s69, s67, 0
	s_cmpk_lt_i32 s88, 0x100
	s_cselect_b64 s[8:9], -1, 0
	s_cmpk_gt_i32 s88, 0xff
	s_waitcnt lgkmcnt(0)
	s_barrier
	s_cbranch_scc1 .LBB0_109
	v_and_b32_e32 v1, 63, v0
	v_cmp_gt_u32_e32 vcc, 48, v1
	s_mov_b32 s5, 0x2aaaaaab
	v_lshl_add_u32 v4, v1, 2, 0
	v_cndmask_b32_e32 v2, 47, v1, vcc
	v_mul_hi_i32 v1, v0, s5
	s_ashr_i32 s0, s12, 6
	v_lshrrev_b32_e32 v3, 31, v1
	v_ashrrev_i32_e32 v1, 3, v1
	s_lshl_b32 s2, s0, 10
	v_add_u32_e32 v3, v1, v3
	s_add_i32 s15, s2, 0
	s_movk_i32 s2, 0xf0
	v_mul_lo_u32 v1, v3, 48
	v_readlane_b32 s16, v254, 1
	s_lshl_b32 s1, s0, 8
	s_mul_i32 s4, s0, 0xc00000
	v_cmp_gt_i32_e64 s[2:3], s2, v0
	v_sub_u32_e32 v0, v0, v1
	s_mul_i32 s12, s0, 0x3c0
	s_movk_i32 s0, 0xc0
	v_readlane_b32 s24, v254, 9
	s_mul_hi_i32 s1, s1, 0xc000
	v_lshl_add_u32 v5, v0, 2, 0
	s_movk_i32 s5, 0x3000
	v_mul_lo_u32 v6, v3, s0
	v_readlane_b32 s17, v254, 2
	v_readlane_b32 s18, v254, 3
	v_readlane_b32 s19, v254, 4
	v_readlane_b32 s20, v254, 5
	v_readlane_b32 s21, v254, 6
	v_readlane_b32 s22, v254, 7
	v_readlane_b32 s23, v254, 8
	v_readlane_b32 s25, v254, 10
	v_readlane_b32 s26, v254, 11
	v_readlane_b32 s27, v254, 12
	v_readlane_b32 s28, v254, 13
	v_readlane_b32 s29, v254, 14
	v_readlane_b32 s30, v254, 15
	v_readlane_b32 s31, v254, 16
	s_add_u32 s0, s24, s4
	s_mov_b32 s14, 0xc000
	v_mul_lo_u32 v1, v3, s5
	s_addc_u32 s1, s25, s1
	s_and_b32 s98, s88, 7
	s_lshl_b32 s98, s98, 5
	s_lshr_b32 s99, s88, 3
	s_or_b32 s98, s98, s99
	v_mad_u64_u32 v[2:3], s[4:5], s98, 48, v[2:3]
	s_mul_i32 s16, s86, 48
	s_mov_b32 s17, 0x18000
	s_mov_b32 s18, 0x24000
	s_mov_b32 s19, 0x30000
	s_mov_b32 s20, 0x3c000
	s_mov_b32 s21, 0x48000
	s_mov_b32 s22, 0x54000
	s_mov_b32 s23, 0x60000
	s_mov_b32 s24, 0x6c000
	s_mov_b32 s25, 0x78000
	s_mov_b32 s26, 0x84000
	s_mov_b32 s27, 0x90000
	s_mov_b32 s28, 0x9c000
	s_mov_b32 s29, 0xa8000
	s_mov_b32 s30, 0xb4000
	v_add_u32_e32 v12, s12, v4
	v_add_u32_e32 v13, v5, v6
	s_mov_b32 s31, s98
	s_branch .LBB0_103
